# FINAL phase: the four X row-quarter loads of a row issued together with counted waits instead of four serialized load/store round trips
# speedup vs baseline: 1.0008x; 1.0008x over previous
; __device__ __forceinline__ void final_phase(Frame& F) {
;     ...
;     for (int r = gw; r < MR; r += NGW) {
;         float* dst;
;         if (r < MP) { const int b = r / TP, tt = r - b * TP; if (tt < NMETA) continue; dst = F.out + O_YP + ((size_t)b * SEQ + (tt - NMETA)) * D; }
;         else dst = F.out + O_YS + (size_t)(r - MP) * D;
;         const float rstd = __builtin_amdgcn_rsqf(ss[r] * (1.0f / D) + EPS);
; #pragma unroll
;         for (int j = 0; j < 4; ++j) { const f32x4 v = ((const f32x4*)(X + (size_t)r * D))[F.lane + 64 * j]; __builtin_nontemporal_store(v * rstd * gv[j], (f32x4*)dst + F.lane + 64 * j); }
;     }
.LBB0_539:
	s_andn2_b64 vcc, exec, s[8:9]
	s_cbranch_vccnz .LBB0_534
	s_add_u32 s8, s74, s2
	s_addc_u32 s9, s75, s3
	global_load_dword v19, v129, s[8:9]
	v_lshl_add_u64 v[20:21], s[74:75], 0, v[16:17]
	v_add_co_u32_e32 v24, vcc, 0x2b00000, v20
	s_nop 1
	v_addc_co_u32_e32 v25, vcc, 0, v21, vcc
	global_load_dwordx4 v[20:23], v[24:25], off
	global_load_dwordx4 v[28:31], v[24:25], off offset:1024
	global_load_dwordx4 v[32:35], v[24:25], off offset:2048
	global_load_dwordx4 v[36:39], v[24:25], off offset:3072
	s_waitcnt vmcnt(4)
	v_fmamk_f32 v19, v19, 0x3a800000, v199
	v_rsq_f32_e32 v26, v19
	s_waitcnt vmcnt(3)
	v_pk_mul_f32 v[22:23], v[22:23], v[26:27] op_sel_hi:[1,0]
	v_pk_mul_f32 v[20:21], v[20:21], v[26:27] op_sel_hi:[1,0]
	v_pk_mul_f32 v[22:23], v[2:3], v[22:23]
	v_pk_mul_f32 v[20:21], v[0:1], v[20:21]
	global_store_dwordx4 v18, v[20:23], s[6:7] nt
	s_waitcnt vmcnt(3)
	v_pk_mul_f32 v[30:31], v[30:31], v[26:27] op_sel_hi:[1,0]
	v_pk_mul_f32 v[28:29], v[28:29], v[26:27] op_sel_hi:[1,0]
	v_pk_mul_f32 v[30:31], v[6:7], v[30:31]
	v_pk_mul_f32 v[28:29], v[4:5], v[28:29]
	global_store_dwordx4 v18, v[28:31], s[6:7] offset:1024 nt
	s_waitcnt vmcnt(3)
	v_pk_mul_f32 v[34:35], v[26:27], v[34:35] op_sel_hi:[0,1]
	v_pk_mul_f32 v[32:33], v[26:27], v[32:33] op_sel_hi:[0,1]
	v_pk_mul_f32 v[34:35], v[10:11], v[34:35]
	v_pk_mul_f32 v[32:33], v[8:9], v[32:33]
	global_store_dwordx4 v18, v[32:35], s[6:7] offset:2048 nt
	s_waitcnt vmcnt(3)
	v_pk_mul_f32 v[38:39], v[26:27], v[38:39] op_sel_hi:[0,1]
	v_pk_mul_f32 v[36:37], v[26:27], v[36:37] op_sel_hi:[0,1]
	v_pk_mul_f32 v[38:39], v[14:15], v[38:39]
	v_pk_mul_f32 v[36:37], v[12:13], v[36:37]
	global_store_dwordx4 v18, v[36:39], s[6:7] offset:3072 nt
	s_branch .LBB0_534
